# gates/merge: wave-group re-alignment barrier moved before the last tile's epilogue so both halves' last epilogues overlap
# speedup vs baseline: 1.0401x; 1.0004x over previous
.LBB0_604:
	s_add_u32 s12, s10, 0xfffc0080
	s_addc_u32 s13, s11, -1
	s_add_i32 s36, 0, 0x10000
	v_add_u32_e32 v139, s36, v137
	ds_read_b128 v[140:143], v139
	ds_read_b128 v[144:147], v139 offset:1024
	ds_read_b128 v[148:151], v139 offset:2048
	ds_read_b128 v[152:155], v139 offset:3072
	s_cmp_eq_u32 s35, 12
	s_cselect_b32 s15, s7, s13
	s_cselect_b32 s14, s6, s12
	s_cselect_b32 s13, s9, s34
	s_cselect_b32 s12, s8, s31
	v_lshl_add_u64 v[188:189], s[10:11], 0, v[132:133]
	s_add_i32 m0, s22, 0xc000
	ds_read_b128 v[156:159], v138
	ds_read_b128 v[160:163], v138 offset:1024
	ds_read_b128 v[164:167], v138 offset:2048
	ds_read_b128 v[168:171], v138 offset:3072
	ds_read_b128 v[172:175], v138 offset:4096
	ds_read_b128 v[176:179], v138 offset:5120
	ds_read_b128 v[180:183], v138 offset:6144
	ds_read_b128 v[184:187], v138 offset:7168
	global_load_lds_dwordx4 v[188:189], off
	v_lshl_add_u64 v[188:189], s[10:11], 0, v[134:135]
	s_add_i32 m0, s22, 0xe000
	s_nop 0
	global_load_lds_dwordx4 v[188:189], off
	s_waitcnt lgkmcnt(8)
	s_barrier
	s_waitcnt lgkmcnt(0)
	s_setprio 1
	s_waitcnt lgkmcnt(0)
	v_mfma_f32_16x16x32_bf16 v[124:127], v[140:143], v[156:159], v[124:127]
	v_mfma_f32_16x16x32_bf16 v[120:123], v[148:151], v[156:159], v[120:123]
	v_mfma_f32_16x16x32_bf16 v[108:111], v[140:143], v[164:167], v[108:111]
	v_mfma_f32_16x16x32_bf16 v[104:107], v[148:151], v[164:167], v[104:107]
	v_mfma_f32_16x16x32_bf16 v[92:95], v[140:143], v[172:175], v[92:95]
	v_mfma_f32_16x16x32_bf16 v[88:91], v[148:151], v[172:175], v[88:91]
	v_mfma_f32_16x16x32_bf16 v[76:79], v[140:143], v[180:183], v[76:79]
	v_mfma_f32_16x16x32_bf16 v[72:75], v[148:151], v[180:183], v[72:75]
	v_mfma_f32_16x16x32_bf16 v[124:127], v[144:147], v[160:163], v[124:127]
	v_mfma_f32_16x16x32_bf16 v[120:123], v[152:155], v[160:163], v[120:123]
	v_mfma_f32_16x16x32_bf16 v[108:111], v[144:147], v[168:171], v[108:111]
	v_mfma_f32_16x16x32_bf16 v[104:107], v[152:155], v[168:171], v[104:107]
	v_mfma_f32_16x16x32_bf16 v[92:95], v[144:147], v[176:179], v[92:95]
	v_mfma_f32_16x16x32_bf16 v[88:91], v[152:155], v[176:179], v[88:91]
	v_mfma_f32_16x16x32_bf16 v[76:79], v[144:147], v[184:187], v[76:79]
	v_mfma_f32_16x16x32_bf16 v[72:75], v[152:155], v[184:187], v[72:75]
	s_setprio 0
	s_barrier
	s_add_i32 s38, 0, 0x14000
	s_add_i32 s36, s36, s21
	v_add_u32_e32 v139, s38, v137
	v_lshl_add_u64 v[192:193], s[12:13], 0, v[130:131]
	s_mov_b32 m0, s36
	ds_read_b128 v[188:191], v139
	ds_read_b128 v[204:207], v139 offset:1024
	ds_read_b128 v[208:211], v139 offset:2048
	ds_read_b128 v[212:215], v139 offset:3072
	global_load_lds_dwordx4 v[192:193], off
	v_lshl_add_u64 v[216:217], s[12:13], 0, v[128:129]
	s_add_i32 m0, s36, 0x2000
	s_nop 0
	global_load_lds_dwordx4 v[216:217], off
	s_barrier
	s_waitcnt lgkmcnt(0)
	s_setprio 1
	s_waitcnt lgkmcnt(0)
	v_mfma_f32_16x16x32_bf16 v[116:119], v[188:191], v[156:159], v[116:119]
	v_mfma_f32_16x16x32_bf16 v[112:115], v[208:211], v[156:159], v[112:115]
	v_mfma_f32_16x16x32_bf16 v[100:103], v[188:191], v[164:167], v[100:103]
	v_mfma_f32_16x16x32_bf16 v[96:99], v[208:211], v[164:167], v[96:99]
	v_mfma_f32_16x16x32_bf16 v[84:87], v[188:191], v[172:175], v[84:87]
	v_mfma_f32_16x16x32_bf16 v[80:83], v[208:211], v[172:175], v[80:83]
	v_mfma_f32_16x16x32_bf16 v[68:71], v[188:191], v[180:183], v[68:71]
	v_mfma_f32_16x16x32_bf16 v[64:67], v[208:211], v[180:183], v[64:67]
	v_mfma_f32_16x16x32_bf16 v[116:119], v[204:207], v[160:163], v[116:119]
	v_mfma_f32_16x16x32_bf16 v[112:115], v[212:215], v[160:163], v[112:115]
	v_mfma_f32_16x16x32_bf16 v[100:103], v[204:207], v[168:171], v[100:103]
	v_mfma_f32_16x16x32_bf16 v[96:99], v[212:215], v[168:171], v[96:99]
	v_mfma_f32_16x16x32_bf16 v[84:87], v[204:207], v[176:179], v[84:87]
	v_mfma_f32_16x16x32_bf16 v[80:83], v[212:215], v[176:179], v[80:83]
	v_mfma_f32_16x16x32_bf16 v[68:71], v[204:207], v[184:187], v[68:71]
	v_mfma_f32_16x16x32_bf16 v[64:67], v[212:215], v[184:187], v[64:67]
	s_setprio 0
	s_mov_b32 m0, s22
	v_lshl_add_u64 v[236:237], s[14:15], 0, v[130:131]
	s_barrier
	ds_read_b128 v[156:159], v138 offset:16384
	ds_read_b128 v[160:163], v138 offset:17408
	ds_read_b128 v[164:167], v138 offset:18432
	ds_read_b128 v[168:171], v138 offset:19456
	ds_read_b128 v[172:175], v138 offset:20480
	ds_read_b128 v[176:179], v138 offset:21504
	ds_read_b128 v[180:183], v138 offset:22528
	ds_read_b128 v[184:187], v138 offset:23552
	global_load_lds_dwordx4 v[236:237], off
	v_lshl_add_u64 v[238:239], s[14:15], 0, v[128:129]
	s_mov_b32 m0, s23
	s_nop 0
	global_load_lds_dwordx4 v[238:239], off
	s_barrier
	s_waitcnt lgkmcnt(0)
	s_setprio 1
	s_waitcnt lgkmcnt(0)
	v_mfma_f32_16x16x32_bf16 v[60:63], v[140:143], v[156:159], v[60:63]
	v_mfma_f32_16x16x32_bf16 v[56:59], v[148:151], v[156:159], v[56:59]
	v_mfma_f32_16x16x32_bf16 v[44:47], v[140:143], v[164:167], v[44:47]
	v_mfma_f32_16x16x32_bf16 v[40:43], v[148:151], v[164:167], v[40:43]
	v_mfma_f32_16x16x32_bf16 v[28:31], v[140:143], v[172:175], v[28:31]
	v_mfma_f32_16x16x32_bf16 v[24:27], v[148:151], v[172:175], v[24:27]
	v_mfma_f32_16x16x32_bf16 v[12:15], v[140:143], v[180:183], v[12:15]
	v_mfma_f32_16x16x32_bf16 v[8:11], v[148:151], v[180:183], v[8:11]
	v_mfma_f32_16x16x32_bf16 v[60:63], v[144:147], v[160:163], v[60:63]
	v_mfma_f32_16x16x32_bf16 v[56:59], v[152:155], v[160:163], v[56:59]
	v_mfma_f32_16x16x32_bf16 v[44:47], v[144:147], v[168:171], v[44:47]
	v_mfma_f32_16x16x32_bf16 v[40:43], v[152:155], v[168:171], v[40:43]
	v_mfma_f32_16x16x32_bf16 v[28:31], v[144:147], v[176:179], v[28:31]
	v_mfma_f32_16x16x32_bf16 v[24:27], v[152:155], v[176:179], v[24:27]
	v_mfma_f32_16x16x32_bf16 v[12:15], v[144:147], v[184:187], v[12:15]
	v_mfma_f32_16x16x32_bf16 v[8:11], v[152:155], v[184:187], v[8:11]
	s_setprio 0
	s_barrier
	s_add_u32 s36, s12, 0x40000
	s_addc_u32 s37, s13, 0
	s_add_i32 s38, s38, s21
	v_lshl_add_u64 v[140:141], s[36:37], 0, v[130:131]
	s_mov_b32 m0, s38
	s_nop 0
	global_load_lds_dwordx4 v[140:141], off
	v_lshl_add_u64 v[140:141], s[36:37], 0, v[128:129]
	s_add_i32 m0, s38, 0x2000
	s_nop 0
	global_load_lds_dwordx4 v[140:141], off
	s_waitcnt vmcnt(6)
	s_barrier
	s_setprio 1
	v_mfma_f32_16x16x32_bf16 v[52:55], v[188:191], v[156:159], v[52:55]
	v_mfma_f32_16x16x32_bf16 v[48:51], v[208:211], v[156:159], v[48:51]
	v_mfma_f32_16x16x32_bf16 v[36:39], v[188:191], v[164:167], v[36:39]
	v_mfma_f32_16x16x32_bf16 v[32:35], v[208:211], v[164:167], v[32:35]
	v_mfma_f32_16x16x32_bf16 v[20:23], v[188:191], v[172:175], v[20:23]
	v_mfma_f32_16x16x32_bf16 v[16:19], v[208:211], v[172:175], v[16:19]
	v_mfma_f32_16x16x32_bf16 v[4:7], v[188:191], v[180:183], v[4:7]
	v_mfma_f32_16x16x32_bf16 v[0:3], v[208:211], v[180:183], v[0:3]
	v_mfma_f32_16x16x32_bf16 v[52:55], v[204:207], v[160:163], v[52:55]
	v_mfma_f32_16x16x32_bf16 v[48:51], v[212:215], v[160:163], v[48:51]
	v_mfma_f32_16x16x32_bf16 v[36:39], v[204:207], v[168:171], v[36:39]
	v_mfma_f32_16x16x32_bf16 v[32:35], v[212:215], v[168:171], v[32:35]
	v_mfma_f32_16x16x32_bf16 v[20:23], v[204:207], v[176:179], v[20:23]
	v_mfma_f32_16x16x32_bf16 v[16:19], v[212:215], v[176:179], v[16:19]
	v_mfma_f32_16x16x32_bf16 v[4:7], v[204:207], v[184:187], v[4:7]
	v_mfma_f32_16x16x32_bf16 v[0:3], v[212:215], v[184:187], v[0:3]
	s_setprio 0
	s_add_i32 s36, 0, 0x18000
	v_add_u32_e32 v139, s36, v137
	s_barrier
	ds_read_b128 v[140:143], v139
	ds_read_b128 v[144:147], v139 offset:1024
	ds_read_b128 v[148:151], v139 offset:2048
	ds_read_b128 v[152:155], v139 offset:3072
	s_add_u32 s14, s14, 0x40000
	s_addc_u32 s15, s15, 0
	s_mov_b32 m0, s24
	v_lshl_add_u64 v[188:189], s[14:15], 0, v[130:131]
	ds_read_b128 v[156:159], v138 offset:32768
	ds_read_b128 v[160:163], v138 offset:33792
	ds_read_b128 v[164:167], v138 offset:34816
	ds_read_b128 v[168:171], v138 offset:35840
	ds_read_b128 v[172:175], v138 offset:36864
	ds_read_b128 v[176:179], v138 offset:37888
	ds_read_b128 v[180:183], v138 offset:38912
	ds_read_b128 v[184:187], v138 offset:39936
	global_load_lds_dwordx4 v[188:189], off
	v_lshl_add_u64 v[188:189], s[14:15], 0, v[128:129]
	s_mov_b32 m0, s25
	s_nop 0
	global_load_lds_dwordx4 v[188:189], off
	s_waitcnt lgkmcnt(8)
	s_barrier
	s_waitcnt lgkmcnt(0)
	s_setprio 1
	s_waitcnt lgkmcnt(0)
	v_mfma_f32_16x16x32_bf16 v[124:127], v[140:143], v[156:159], v[124:127]
	v_mfma_f32_16x16x32_bf16 v[120:123], v[148:151], v[156:159], v[120:123]
	v_mfma_f32_16x16x32_bf16 v[108:111], v[140:143], v[164:167], v[108:111]
	v_mfma_f32_16x16x32_bf16 v[104:107], v[148:151], v[164:167], v[104:107]
	v_mfma_f32_16x16x32_bf16 v[92:95], v[140:143], v[172:175], v[92:95]
	v_mfma_f32_16x16x32_bf16 v[88:91], v[148:151], v[172:175], v[88:91]
	v_mfma_f32_16x16x32_bf16 v[76:79], v[140:143], v[180:183], v[76:79]
	v_mfma_f32_16x16x32_bf16 v[72:75], v[148:151], v[180:183], v[72:75]
	v_mfma_f32_16x16x32_bf16 v[124:127], v[144:147], v[160:163], v[124:127]
	v_mfma_f32_16x16x32_bf16 v[120:123], v[152:155], v[160:163], v[120:123]
	v_mfma_f32_16x16x32_bf16 v[108:111], v[144:147], v[168:171], v[108:111]
	v_mfma_f32_16x16x32_bf16 v[104:107], v[152:155], v[168:171], v[104:107]
	v_mfma_f32_16x16x32_bf16 v[92:95], v[144:147], v[176:179], v[92:95]
	v_mfma_f32_16x16x32_bf16 v[88:91], v[152:155], v[176:179], v[88:91]
	v_mfma_f32_16x16x32_bf16 v[76:79], v[144:147], v[184:187], v[76:79]
	v_mfma_f32_16x16x32_bf16 v[72:75], v[152:155], v[184:187], v[72:75]
	s_setprio 0
	s_barrier
	s_add_i32 s14, 0, 0x1c000
	s_add_i32 s15, s36, s21
	v_add_u32_e32 v139, s14, v137
	v_lshl_add_u64 v[192:193], v[192:193], 0, s[82:83]
	s_mov_b32 m0, s15
	ds_read_b128 v[188:191], v139
	ds_read_b128 v[204:207], v139 offset:1024
	ds_read_b128 v[208:211], v139 offset:2048
	ds_read_b128 v[212:215], v139 offset:3072
	global_load_lds_dwordx4 v[192:193], off
	v_lshl_add_u64 v[192:193], v[216:217], 0, s[82:83]
	s_add_i32 m0, s15, 0x2000
	s_nop 0
	global_load_lds_dwordx4 v[192:193], off
	s_barrier
	s_waitcnt lgkmcnt(0)
	s_setprio 1
	s_waitcnt lgkmcnt(0)
	v_mfma_f32_16x16x32_bf16 v[116:119], v[188:191], v[156:159], v[116:119]
	v_mfma_f32_16x16x32_bf16 v[112:115], v[208:211], v[156:159], v[112:115]
	v_mfma_f32_16x16x32_bf16 v[100:103], v[188:191], v[164:167], v[100:103]
	v_mfma_f32_16x16x32_bf16 v[96:99], v[208:211], v[164:167], v[96:99]
	v_mfma_f32_16x16x32_bf16 v[84:87], v[188:191], v[172:175], v[84:87]
	v_mfma_f32_16x16x32_bf16 v[80:83], v[208:211], v[172:175], v[80:83]
	v_mfma_f32_16x16x32_bf16 v[68:71], v[188:191], v[180:183], v[68:71]
	v_mfma_f32_16x16x32_bf16 v[64:67], v[208:211], v[180:183], v[64:67]
	v_mfma_f32_16x16x32_bf16 v[116:119], v[204:207], v[160:163], v[116:119]
	v_mfma_f32_16x16x32_bf16 v[112:115], v[212:215], v[160:163], v[112:115]
	v_mfma_f32_16x16x32_bf16 v[100:103], v[204:207], v[168:171], v[100:103]
	v_mfma_f32_16x16x32_bf16 v[96:99], v[212:215], v[168:171], v[96:99]
	v_mfma_f32_16x16x32_bf16 v[84:87], v[204:207], v[176:179], v[84:87]
	v_mfma_f32_16x16x32_bf16 v[80:83], v[212:215], v[176:179], v[80:83]
	v_mfma_f32_16x16x32_bf16 v[68:71], v[204:207], v[184:187], v[68:71]
	v_mfma_f32_16x16x32_bf16 v[64:67], v[212:215], v[184:187], v[64:67]
	s_setprio 0
	s_mov_b32 m0, s26
	v_lshl_add_u64 v[192:193], v[236:237], 0, s[82:83]
	s_barrier
	ds_read_b128 v[156:159], v138 offset:49152
	ds_read_b128 v[160:163], v138 offset:50176
	ds_read_b128 v[164:167], v138 offset:51200
	ds_read_b128 v[168:171], v138 offset:52224
	ds_read_b128 v[172:175], v138 offset:53248
	ds_read_b128 v[176:179], v138 offset:54272
	ds_read_b128 v[180:183], v138 offset:55296
	ds_read_b128 v[184:187], v138 offset:56320
	global_load_lds_dwordx4 v[192:193], off
	v_lshl_add_u64 v[192:193], v[238:239], 0, s[82:83]
	s_mov_b32 m0, s27
	s_nop 0
	global_load_lds_dwordx4 v[192:193], off
	s_barrier
	s_waitcnt lgkmcnt(0)
	s_setprio 1
	s_waitcnt lgkmcnt(0)
	v_mfma_f32_16x16x32_bf16 v[60:63], v[140:143], v[156:159], v[60:63]
	v_mfma_f32_16x16x32_bf16 v[56:59], v[148:151], v[156:159], v[56:59]
	v_mfma_f32_16x16x32_bf16 v[44:47], v[140:143], v[164:167], v[44:47]
	v_mfma_f32_16x16x32_bf16 v[40:43], v[148:151], v[164:167], v[40:43]
	v_mfma_f32_16x16x32_bf16 v[28:31], v[140:143], v[172:175], v[28:31]
	v_mfma_f32_16x16x32_bf16 v[24:27], v[148:151], v[172:175], v[24:27]
	v_mfma_f32_16x16x32_bf16 v[12:15], v[140:143], v[180:183], v[12:15]
	v_mfma_f32_16x16x32_bf16 v[8:11], v[148:151], v[180:183], v[8:11]
	v_mfma_f32_16x16x32_bf16 v[60:63], v[144:147], v[160:163], v[60:63]
	v_mfma_f32_16x16x32_bf16 v[56:59], v[152:155], v[160:163], v[56:59]
	v_mfma_f32_16x16x32_bf16 v[44:47], v[144:147], v[168:171], v[44:47]
	v_mfma_f32_16x16x32_bf16 v[40:43], v[152:155], v[168:171], v[40:43]
	v_mfma_f32_16x16x32_bf16 v[28:31], v[144:147], v[176:179], v[28:31]
	v_mfma_f32_16x16x32_bf16 v[24:27], v[152:155], v[176:179], v[24:27]
	v_mfma_f32_16x16x32_bf16 v[12:15], v[144:147], v[184:187], v[12:15]
	v_mfma_f32_16x16x32_bf16 v[8:11], v[152:155], v[184:187], v[8:11]
	s_setprio 0
	s_barrier
	s_add_u32 s12, s12, 0x40080
	s_addc_u32 s13, s13, 0
	s_add_i32 s14, s14, s21
	v_lshl_add_u64 v[140:141], s[12:13], 0, v[130:131]
	s_mov_b32 m0, s14
	s_nop 0
	global_load_lds_dwordx4 v[140:141], off
	v_lshl_add_u64 v[140:141], s[12:13], 0, v[128:129]
	s_add_i32 m0, s14, 0x2000
	s_nop 0
	global_load_lds_dwordx4 v[140:141], off
	s_waitcnt vmcnt(6)
	s_barrier
	s_setprio 1
	v_mfma_f32_16x16x32_bf16 v[52:55], v[188:191], v[156:159], v[52:55]
	v_mfma_f32_16x16x32_bf16 v[48:51], v[208:211], v[156:159], v[48:51]
	v_mfma_f32_16x16x32_bf16 v[36:39], v[188:191], v[164:167], v[36:39]
	v_mfma_f32_16x16x32_bf16 v[32:35], v[208:211], v[164:167], v[32:35]
	v_mfma_f32_16x16x32_bf16 v[20:23], v[188:191], v[172:175], v[20:23]
	v_mfma_f32_16x16x32_bf16 v[16:19], v[208:211], v[172:175], v[16:19]
	v_mfma_f32_16x16x32_bf16 v[4:7], v[188:191], v[180:183], v[4:7]
	v_mfma_f32_16x16x32_bf16 v[0:3], v[208:211], v[180:183], v[0:3]
	v_mfma_f32_16x16x32_bf16 v[52:55], v[204:207], v[160:163], v[52:55]
	v_mfma_f32_16x16x32_bf16 v[48:51], v[212:215], v[160:163], v[48:51]
	v_mfma_f32_16x16x32_bf16 v[36:39], v[204:207], v[168:171], v[36:39]
	v_mfma_f32_16x16x32_bf16 v[32:35], v[212:215], v[168:171], v[32:35]
	v_mfma_f32_16x16x32_bf16 v[20:23], v[204:207], v[176:179], v[20:23]
	v_mfma_f32_16x16x32_bf16 v[16:19], v[212:215], v[176:179], v[16:19]
	v_mfma_f32_16x16x32_bf16 v[4:7], v[204:207], v[184:187], v[4:7]
	v_mfma_f32_16x16x32_bf16 v[0:3], v[212:215], v[184:187], v[0:3]
	s_setprio 0
	s_add_i32 s35, s35, 2
	s_add_u32 s10, s10, 0x100
	s_addc_u32 s11, s11, 0
	s_add_u32 s31, s31, 0x100
	s_addc_u32 s34, s34, 0
	s_cmp_gt_u32 s35, 13
	s_barrier
	s_cbranch_scc0 .LBB0_604
	s_and_b64 vcc, exec, s[4:5]
	s_cbranch_vccz .Lal_gates
	s_cmpk_gt_u32 s16, 0xff
	s_cbranch_scc1 .Lal_gates
	s_barrier
.Lal_gates:
	v_exp_f32_e32 v124, v124
	v_exp_f32_e32 v125, v125
	v_exp_f32_e32 v120, v120
	v_exp_f32_e32 v121, v121
	v_add_f32_e32 v124, 1.0, v124
	v_add_f32_e32 v125, 1.0, v125
	v_rcp_f32_e32 v124, v124
	v_rcp_f32_e32 v125, v125
	s_nop 1
	v_cvt_pk_bf16_f32 v124, v124, v125
	v_exp_f32_e32 v125, v126
	v_exp_f32_e32 v126, v127
	v_add_f32_e32 v120, 1.0, v120
	v_add_f32_e32 v121, 1.0, v121
	v_add_f32_e32 v125, 1.0, v125
	v_add_f32_e32 v126, 1.0, v126
	v_rcp_f32_e32 v125, v125
	v_rcp_f32_e32 v126, v126
	v_rcp_f32_e32 v120, v120
	v_rcp_f32_e32 v121, v121
	s_nop 1
	v_cvt_pk_bf16_f32 v125, v125, v126
	s_nop 1
	v_cvt_pk_bf16_f32 v126, v120, v121
	v_exp_f32_e32 v120, v122
	v_exp_f32_e32 v121, v123
	s_lshl_b32 s10, s3, 8
	v_exp_f32_e32 v116, v116
	v_add_f32_e32 v120, 1.0, v120
	v_add_f32_e32 v121, 1.0, v121
	v_rcp_f32_e32 v120, v120
	v_rcp_f32_e32 v121, v121
	v_exp_f32_e32 v117, v117
	v_lshl_add_u32 v139, s2, 8, v136
	s_ashr_i32 s11, s10, 31
	s_nop 1
	v_cvt_pk_bf16_f32 v127, v120, v121
	v_mov_b64_e32 v[120:121], s[0:1]
	v_mad_i64_i32 v[122:123], s[2:3], v139, s81, v[120:121]
	s_lshl_b64 s[10:11], s[10:11], 1
	v_lshl_add_u64 v[122:123], v[122:123], 0, s[10:11]
	v_lshl_add_u64 v[122:123], v[122:123], 0, s[90:91]
	v_add_f32_e32 v116, 1.0, v116
	v_add_f32_e32 v117, 1.0, v117
	v_lshl_add_u64 v[122:123], v[122:123], 0, v[194:195]
	v_rcp_f32_e32 v116, v116
	v_rcp_f32_e32 v117, v117
	global_store_dwordx4 v[122:123], v[124:127], off
	s_nop 1
	v_cvt_pk_bf16_f32 v116, v116, v117
	v_exp_f32_e32 v117, v118
	v_exp_f32_e32 v118, v119
	v_exp_f32_e32 v112, v112
	v_exp_f32_e32 v113, v113
	v_add_f32_e32 v117, 1.0, v117
	v_add_f32_e32 v118, 1.0, v118
	v_add_f32_e32 v112, 1.0, v112
	v_add_f32_e32 v113, 1.0, v113
	v_rcp_f32_e32 v117, v117
	v_rcp_f32_e32 v118, v118
	v_rcp_f32_e32 v112, v112
	v_rcp_f32_e32 v113, v113
	v_exp_f32_e32 v108, v108
	v_exp_f32_e32 v109, v109
	s_nop 1
	v_cvt_pk_bf16_f32 v117, v117, v118
	s_nop 1
	v_cvt_pk_bf16_f32 v118, v112, v113
	v_exp_f32_e32 v112, v114
	v_exp_f32_e32 v113, v115
	v_add_f32_e32 v108, 1.0, v108
	v_add_f32_e32 v109, 1.0, v109
	v_add_f32_e32 v112, 1.0, v112
	v_add_f32_e32 v113, 1.0, v113
	v_rcp_f32_e32 v108, v108
	v_rcp_f32_e32 v109, v109
	v_rcp_f32_e32 v112, v112
	v_rcp_f32_e32 v113, v113
	s_nop 1
	v_cvt_pk_bf16_f32 v119, v112, v113
	global_store_dwordx4 v[122:123], v[116:119], off offset:256
	s_nop 1
	v_cvt_pk_bf16_f32 v108, v108, v109
	v_exp_f32_e32 v109, v110
	v_exp_f32_e32 v110, v111
	v_exp_f32_e32 v104, v104
	v_exp_f32_e32 v105, v105
	v_add_f32_e32 v109, 1.0, v109
	v_add_f32_e32 v110, 1.0, v110
	v_add_f32_e32 v104, 1.0, v104
	v_add_f32_e32 v105, 1.0, v105
	v_rcp_f32_e32 v109, v109
	v_rcp_f32_e32 v110, v110
	v_rcp_f32_e32 v104, v104
	v_rcp_f32_e32 v105, v105
	s_nop 1
	v_cvt_pk_bf16_f32 v109, v109, v110
	s_nop 1
	v_cvt_pk_bf16_f32 v110, v104, v105
	v_exp_f32_e32 v104, v106
	v_exp_f32_e32 v105, v107
	v_exp_f32_e32 v100, v100
	v_exp_f32_e32 v101, v101
	v_add_f32_e32 v104, 1.0, v104
	v_add_f32_e32 v105, 1.0, v105
	v_or_b32_e32 v112, 16, v139
	v_rcp_f32_e32 v104, v104
	v_rcp_f32_e32 v105, v105
	s_nop 1
	v_cvt_pk_bf16_f32 v111, v104, v105
	v_mad_i64_i32 v[104:105], s[2:3], v112, s81, v[120:121]
	v_lshl_add_u64 v[104:105], v[104:105], 0, s[10:11]
	v_lshl_add_u64 v[104:105], v[104:105], 0, s[90:91]
	v_add_f32_e32 v100, 1.0, v100
	v_add_f32_e32 v101, 1.0, v101
	v_lshl_add_u64 v[104:105], v[104:105], 0, v[194:195]
	v_rcp_f32_e32 v100, v100
	v_rcp_f32_e32 v101, v101
	global_store_dwordx4 v[104:105], v[108:111], off
	s_nop 1
	v_cvt_pk_bf16_f32 v100, v100, v101
	v_exp_f32_e32 v101, v102
	v_exp_f32_e32 v102, v103
	v_exp_f32_e32 v96, v96
	v_exp_f32_e32 v97, v97
	v_add_f32_e32 v101, 1.0, v101
	v_add_f32_e32 v102, 1.0, v102
	v_add_f32_e32 v96, 1.0, v96
	v_add_f32_e32 v97, 1.0, v97
	v_rcp_f32_e32 v101, v101
	v_rcp_f32_e32 v102, v102
	v_rcp_f32_e32 v96, v96
	v_rcp_f32_e32 v97, v97
	v_exp_f32_e32 v92, v92
	v_exp_f32_e32 v93, v93
	s_nop 1
	v_cvt_pk_bf16_f32 v101, v101, v102
	s_nop 1
	v_cvt_pk_bf16_f32 v102, v96, v97
	v_exp_f32_e32 v96, v98
	v_exp_f32_e32 v97, v99
	v_add_f32_e32 v92, 1.0, v92
	v_add_f32_e32 v93, 1.0, v93
	v_add_f32_e32 v96, 1.0, v96
	v_add_f32_e32 v97, 1.0, v97
	v_rcp_f32_e32 v92, v92
	v_rcp_f32_e32 v93, v93
	v_rcp_f32_e32 v96, v96
	v_rcp_f32_e32 v97, v97
	s_nop 1
	v_cvt_pk_bf16_f32 v103, v96, v97
	global_store_dwordx4 v[104:105], v[100:103], off offset:256
	s_nop 1
	v_cvt_pk_bf16_f32 v92, v92, v93
	v_exp_f32_e32 v93, v94
	v_exp_f32_e32 v94, v95
	v_exp_f32_e32 v88, v88
	v_exp_f32_e32 v89, v89
	v_add_f32_e32 v93, 1.0, v93
	v_add_f32_e32 v94, 1.0, v94
	v_add_f32_e32 v88, 1.0, v88
	v_add_f32_e32 v89, 1.0, v89
	v_rcp_f32_e32 v93, v93
	v_rcp_f32_e32 v94, v94
	v_rcp_f32_e32 v88, v88
	v_rcp_f32_e32 v89, v89
	s_nop 1
	v_cvt_pk_bf16_f32 v93, v93, v94
	s_nop 1
	v_cvt_pk_bf16_f32 v94, v88, v89
	v_exp_f32_e32 v88, v90
	v_exp_f32_e32 v89, v91
	v_exp_f32_e32 v84, v84
	v_exp_f32_e32 v85, v85
	v_add_f32_e32 v88, 1.0, v88
	v_add_f32_e32 v89, 1.0, v89
	v_or_b32_e32 v96, 32, v139
	v_rcp_f32_e32 v88, v88
	v_rcp_f32_e32 v89, v89
	s_nop 1
	v_cvt_pk_bf16_f32 v95, v88, v89
	v_mad_i64_i32 v[88:89], s[2:3], v96, s81, v[120:121]
	v_lshl_add_u64 v[88:89], v[88:89], 0, s[10:11]
	v_lshl_add_u64 v[88:89], v[88:89], 0, s[90:91]
	v_add_f32_e32 v84, 1.0, v84
	v_add_f32_e32 v85, 1.0, v85
	v_lshl_add_u64 v[88:89], v[88:89], 0, v[194:195]
	v_rcp_f32_e32 v84, v84
	v_rcp_f32_e32 v85, v85
	global_store_dwordx4 v[88:89], v[92:95], off
	s_nop 1
	v_cvt_pk_bf16_f32 v84, v84, v85
	v_exp_f32_e32 v85, v86
	v_exp_f32_e32 v86, v87
	v_exp_f32_e32 v80, v80
	v_exp_f32_e32 v81, v81
	v_add_f32_e32 v85, 1.0, v85
	v_add_f32_e32 v86, 1.0, v86
	v_add_f32_e32 v80, 1.0, v80
	v_add_f32_e32 v81, 1.0, v81
	v_rcp_f32_e32 v85, v85
	v_rcp_f32_e32 v86, v86
	v_rcp_f32_e32 v80, v80
	v_rcp_f32_e32 v81, v81
	v_exp_f32_e32 v76, v76
	v_exp_f32_e32 v77, v77
	s_nop 1
	v_cvt_pk_bf16_f32 v85, v85, v86
	s_nop 1
	v_cvt_pk_bf16_f32 v86, v80, v81
	v_exp_f32_e32 v80, v82
	v_exp_f32_e32 v81, v83
	v_add_f32_e32 v76, 1.0, v76
	v_add_f32_e32 v77, 1.0, v77
	v_add_f32_e32 v80, 1.0, v80
	v_add_f32_e32 v81, 1.0, v81
	v_rcp_f32_e32 v76, v76
	v_rcp_f32_e32 v77, v77
	v_rcp_f32_e32 v80, v80
	v_rcp_f32_e32 v81, v81
	s_nop 1
	v_cvt_pk_bf16_f32 v87, v80, v81
	global_store_dwordx4 v[88:89], v[84:87], off offset:256
	s_nop 1
	v_cvt_pk_bf16_f32 v76, v76, v77
	v_exp_f32_e32 v77, v78
	v_exp_f32_e32 v78, v79
	v_exp_f32_e32 v72, v72
	v_exp_f32_e32 v73, v73
	v_add_f32_e32 v77, 1.0, v77
	v_add_f32_e32 v78, 1.0, v78
	v_add_f32_e32 v72, 1.0, v72
	v_add_f32_e32 v73, 1.0, v73
	v_rcp_f32_e32 v77, v77
	v_rcp_f32_e32 v78, v78
	v_rcp_f32_e32 v72, v72
	v_rcp_f32_e32 v73, v73
	s_nop 1
	v_cvt_pk_bf16_f32 v77, v77, v78
	s_nop 1
	v_cvt_pk_bf16_f32 v78, v72, v73
	v_exp_f32_e32 v72, v74
	v_exp_f32_e32 v73, v75
	v_exp_f32_e32 v68, v68
	v_exp_f32_e32 v69, v69
	v_add_f32_e32 v72, 1.0, v72
	v_add_f32_e32 v73, 1.0, v73
	v_or_b32_e32 v80, 48, v139
	v_rcp_f32_e32 v72, v72
	v_rcp_f32_e32 v73, v73
	s_nop 1
	v_cvt_pk_bf16_f32 v79, v72, v73
	v_mad_i64_i32 v[72:73], s[2:3], v80, s81, v[120:121]
	v_lshl_add_u64 v[72:73], v[72:73], 0, s[10:11]
	v_lshl_add_u64 v[72:73], v[72:73], 0, s[90:91]
	v_add_f32_e32 v68, 1.0, v68
	v_add_f32_e32 v69, 1.0, v69
	v_lshl_add_u64 v[72:73], v[72:73], 0, v[194:195]
	v_rcp_f32_e32 v68, v68
	v_rcp_f32_e32 v69, v69
	global_store_dwordx4 v[72:73], v[76:79], off
	s_nop 1
	v_cvt_pk_bf16_f32 v68, v68, v69
	v_exp_f32_e32 v69, v70
	v_exp_f32_e32 v70, v71
	v_exp_f32_e32 v64, v64
	v_exp_f32_e32 v65, v65
	v_add_f32_e32 v69, 1.0, v69
	v_add_f32_e32 v70, 1.0, v70
	v_add_f32_e32 v64, 1.0, v64
	v_add_f32_e32 v65, 1.0, v65
	v_rcp_f32_e32 v69, v69
	v_rcp_f32_e32 v70, v70
	v_rcp_f32_e32 v64, v64
	v_rcp_f32_e32 v65, v65
	v_exp_f32_e32 v60, v60
	v_exp_f32_e32 v61, v61
	s_nop 1
	v_cvt_pk_bf16_f32 v69, v69, v70
	s_nop 1
	v_cvt_pk_bf16_f32 v70, v64, v65
	v_exp_f32_e32 v64, v66
	v_exp_f32_e32 v65, v67
	v_add_f32_e32 v60, 1.0, v60
	v_add_f32_e32 v61, 1.0, v61
	v_add_f32_e32 v64, 1.0, v64
	v_add_f32_e32 v65, 1.0, v65
	v_rcp_f32_e32 v60, v60
	v_rcp_f32_e32 v61, v61
	v_rcp_f32_e32 v64, v64
	v_rcp_f32_e32 v65, v65
	s_nop 1
	v_cvt_pk_bf16_f32 v71, v64, v65
	global_store_dwordx4 v[72:73], v[68:71], off offset:256
	s_nop 1
	v_cvt_pk_bf16_f32 v60, v60, v61
	v_exp_f32_e32 v61, v62
	v_exp_f32_e32 v62, v63
	v_exp_f32_e32 v56, v56
	v_exp_f32_e32 v57, v57
	v_add_f32_e32 v61, 1.0, v61
	v_add_f32_e32 v62, 1.0, v62
	v_add_f32_e32 v56, 1.0, v56
	v_add_f32_e32 v57, 1.0, v57
	v_rcp_f32_e32 v61, v61
	v_rcp_f32_e32 v62, v62
	v_rcp_f32_e32 v56, v56
	v_rcp_f32_e32 v57, v57
	s_nop 1
	v_cvt_pk_bf16_f32 v61, v61, v62
	s_nop 1
	v_cvt_pk_bf16_f32 v62, v56, v57
	v_exp_f32_e32 v56, v58
	v_exp_f32_e32 v57, v59
	v_exp_f32_e32 v52, v52
	v_exp_f32_e32 v53, v53
	v_add_f32_e32 v56, 1.0, v56
	v_add_f32_e32 v57, 1.0, v57
	v_add_u32_e32 v64, 0x80, v139
	v_rcp_f32_e32 v56, v56
	v_rcp_f32_e32 v57, v57
	s_nop 1
	v_cvt_pk_bf16_f32 v63, v56, v57
	v_mad_i64_i32 v[56:57], s[2:3], v64, s81, v[120:121]
	v_lshl_add_u64 v[56:57], v[56:57], 0, s[10:11]
	v_lshl_add_u64 v[56:57], v[56:57], 0, s[90:91]
	v_add_f32_e32 v52, 1.0, v52
	v_add_f32_e32 v53, 1.0, v53
	v_lshl_add_u64 v[56:57], v[56:57], 0, v[194:195]
	v_rcp_f32_e32 v52, v52
	v_rcp_f32_e32 v53, v53
	global_store_dwordx4 v[56:57], v[60:63], off
	s_nop 1
	v_cvt_pk_bf16_f32 v52, v52, v53
	v_exp_f32_e32 v53, v54
	v_exp_f32_e32 v54, v55
	v_exp_f32_e32 v48, v48
	v_exp_f32_e32 v49, v49
	v_add_f32_e32 v53, 1.0, v53
	v_add_f32_e32 v54, 1.0, v54
	v_add_f32_e32 v48, 1.0, v48
	v_add_f32_e32 v49, 1.0, v49
	v_rcp_f32_e32 v53, v53
	v_rcp_f32_e32 v54, v54
	v_rcp_f32_e32 v48, v48
	v_rcp_f32_e32 v49, v49
	v_exp_f32_e32 v44, v44
	v_exp_f32_e32 v45, v45
	s_nop 1
	v_cvt_pk_bf16_f32 v53, v53, v54
	s_nop 1
	v_cvt_pk_bf16_f32 v54, v48, v49
	v_exp_f32_e32 v48, v50
	v_exp_f32_e32 v49, v51
	v_add_f32_e32 v44, 1.0, v44
	v_add_f32_e32 v45, 1.0, v45
	v_add_f32_e32 v48, 1.0, v48
	v_add_f32_e32 v49, 1.0, v49
	v_rcp_f32_e32 v44, v44
	v_rcp_f32_e32 v45, v45
	v_rcp_f32_e32 v48, v48
	v_rcp_f32_e32 v49, v49
	s_nop 1
	v_cvt_pk_bf16_f32 v55, v48, v49
	global_store_dwordx4 v[56:57], v[52:55], off offset:256
	s_nop 1
	v_cvt_pk_bf16_f32 v44, v44, v45
	v_exp_f32_e32 v45, v46
	v_exp_f32_e32 v46, v47
	v_exp_f32_e32 v40, v40
	v_exp_f32_e32 v41, v41
	v_add_f32_e32 v45, 1.0, v45
	v_add_f32_e32 v46, 1.0, v46
	v_add_f32_e32 v40, 1.0, v40
	v_add_f32_e32 v41, 1.0, v41
	v_rcp_f32_e32 v45, v45
	v_rcp_f32_e32 v46, v46
	v_rcp_f32_e32 v40, v40
	v_rcp_f32_e32 v41, v41
	s_nop 1
	v_cvt_pk_bf16_f32 v45, v45, v46
	s_nop 1
	v_cvt_pk_bf16_f32 v46, v40, v41
	v_exp_f32_e32 v40, v42
	v_exp_f32_e32 v41, v43
	v_exp_f32_e32 v36, v36
	v_exp_f32_e32 v37, v37
	v_add_f32_e32 v40, 1.0, v40
	v_add_f32_e32 v41, 1.0, v41
	v_add_u32_e32 v48, 0x90, v139
	v_rcp_f32_e32 v40, v40
	v_rcp_f32_e32 v41, v41
	s_nop 1
	v_cvt_pk_bf16_f32 v47, v40, v41
	v_mad_i64_i32 v[40:41], s[2:3], v48, s81, v[120:121]
	v_lshl_add_u64 v[40:41], v[40:41], 0, s[10:11]
	v_lshl_add_u64 v[40:41], v[40:41], 0, s[90:91]
	v_add_f32_e32 v36, 1.0, v36
	v_add_f32_e32 v37, 1.0, v37
	v_lshl_add_u64 v[40:41], v[40:41], 0, v[194:195]
	v_rcp_f32_e32 v36, v36
	v_rcp_f32_e32 v37, v37
	global_store_dwordx4 v[40:41], v[44:47], off
	s_nop 1
	v_cvt_pk_bf16_f32 v36, v36, v37
	v_exp_f32_e32 v37, v38
	v_exp_f32_e32 v38, v39
	v_exp_f32_e32 v32, v32
	v_exp_f32_e32 v33, v33
	v_add_f32_e32 v37, 1.0, v37
	v_add_f32_e32 v38, 1.0, v38
	v_add_f32_e32 v32, 1.0, v32
	v_add_f32_e32 v33, 1.0, v33
	v_rcp_f32_e32 v37, v37
	v_rcp_f32_e32 v38, v38
	v_rcp_f32_e32 v32, v32
	v_rcp_f32_e32 v33, v33
	v_exp_f32_e32 v28, v28
	v_exp_f32_e32 v29, v29
	s_nop 1
	v_cvt_pk_bf16_f32 v37, v37, v38
	s_nop 1
	v_cvt_pk_bf16_f32 v38, v32, v33
	v_exp_f32_e32 v32, v34
	v_exp_f32_e32 v33, v35
	v_add_f32_e32 v28, 1.0, v28
	v_add_f32_e32 v29, 1.0, v29
	v_add_f32_e32 v32, 1.0, v32
	v_add_f32_e32 v33, 1.0, v33
	v_rcp_f32_e32 v28, v28
	v_rcp_f32_e32 v29, v29
	v_rcp_f32_e32 v32, v32
	v_rcp_f32_e32 v33, v33
	s_nop 1
	v_cvt_pk_bf16_f32 v39, v32, v33
	global_store_dwordx4 v[40:41], v[36:39], off offset:256
	s_nop 1
	v_cvt_pk_bf16_f32 v28, v28, v29
	v_exp_f32_e32 v29, v30
	v_exp_f32_e32 v30, v31
	v_exp_f32_e32 v24, v24
	v_exp_f32_e32 v25, v25
	v_add_f32_e32 v29, 1.0, v29
	v_add_f32_e32 v30, 1.0, v30
	v_add_f32_e32 v24, 1.0, v24
	v_add_f32_e32 v25, 1.0, v25
	v_rcp_f32_e32 v29, v29
	v_rcp_f32_e32 v30, v30
	v_rcp_f32_e32 v24, v24
	v_rcp_f32_e32 v25, v25
	s_nop 1
	v_cvt_pk_bf16_f32 v29, v29, v30
	s_nop 1
	v_cvt_pk_bf16_f32 v30, v24, v25
	v_exp_f32_e32 v24, v26
	v_exp_f32_e32 v25, v27
	v_exp_f32_e32 v20, v20
	v_exp_f32_e32 v21, v21
	v_add_f32_e32 v24, 1.0, v24
	v_add_f32_e32 v25, 1.0, v25
	v_add_u32_e32 v32, 0xa0, v139
	v_rcp_f32_e32 v24, v24
	v_rcp_f32_e32 v25, v25
	s_nop 1
	v_cvt_pk_bf16_f32 v31, v24, v25
	v_mad_i64_i32 v[24:25], s[2:3], v32, s81, v[120:121]
	v_lshl_add_u64 v[24:25], v[24:25], 0, s[10:11]
	v_lshl_add_u64 v[24:25], v[24:25], 0, s[90:91]
	v_add_f32_e32 v20, 1.0, v20
	v_add_f32_e32 v21, 1.0, v21
	v_lshl_add_u64 v[24:25], v[24:25], 0, v[194:195]
	v_rcp_f32_e32 v20, v20
	v_rcp_f32_e32 v21, v21
	global_store_dwordx4 v[24:25], v[28:31], off
	s_nop 1
	v_cvt_pk_bf16_f32 v20, v20, v21
	v_exp_f32_e32 v21, v22
	v_exp_f32_e32 v22, v23
	v_exp_f32_e32 v16, v16
	v_exp_f32_e32 v17, v17
	v_add_f32_e32 v21, 1.0, v21
	v_add_f32_e32 v22, 1.0, v22
	v_add_f32_e32 v16, 1.0, v16
	v_add_f32_e32 v17, 1.0, v17
	v_rcp_f32_e32 v21, v21
	v_rcp_f32_e32 v22, v22
	v_rcp_f32_e32 v16, v16
	v_rcp_f32_e32 v17, v17
	v_exp_f32_e32 v12, v12
	v_exp_f32_e32 v13, v13
	s_nop 1
	v_cvt_pk_bf16_f32 v21, v21, v22
	s_nop 1
	v_cvt_pk_bf16_f32 v22, v16, v17
	v_exp_f32_e32 v16, v18
	v_exp_f32_e32 v17, v19
	v_add_f32_e32 v12, 1.0, v12
	v_add_f32_e32 v13, 1.0, v13
	v_add_f32_e32 v16, 1.0, v16
	v_add_f32_e32 v17, 1.0, v17
	v_rcp_f32_e32 v12, v12
	v_rcp_f32_e32 v13, v13
	v_rcp_f32_e32 v16, v16
	v_rcp_f32_e32 v17, v17
	s_nop 1
	v_cvt_pk_bf16_f32 v23, v16, v17
	global_store_dwordx4 v[24:25], v[20:23], off offset:256
	s_nop 1
	v_cvt_pk_bf16_f32 v12, v12, v13
	v_exp_f32_e32 v13, v14
	v_exp_f32_e32 v14, v15
	v_exp_f32_e32 v8, v8
	v_exp_f32_e32 v9, v9
	v_add_f32_e32 v13, 1.0, v13
	v_add_f32_e32 v14, 1.0, v14
	v_add_f32_e32 v8, 1.0, v8
	v_add_f32_e32 v9, 1.0, v9
	v_rcp_f32_e32 v13, v13
	v_rcp_f32_e32 v14, v14
	v_rcp_f32_e32 v8, v8
	v_rcp_f32_e32 v9, v9
	s_nop 1
	v_cvt_pk_bf16_f32 v13, v13, v14
	s_nop 1
	v_cvt_pk_bf16_f32 v14, v8, v9
	v_exp_f32_e32 v8, v10
	v_exp_f32_e32 v9, v11
	v_exp_f32_e32 v4, v4
	v_exp_f32_e32 v5, v5
	v_add_f32_e32 v8, 1.0, v8
	v_add_f32_e32 v9, 1.0, v9
	v_add_u32_e32 v16, 0xb0, v139
	v_rcp_f32_e32 v8, v8
	v_rcp_f32_e32 v9, v9
	s_nop 1
	v_cvt_pk_bf16_f32 v15, v8, v9
	v_mad_i64_i32 v[8:9], s[2:3], v16, s81, v[120:121]
	v_lshl_add_u64 v[8:9], v[8:9], 0, s[10:11]
	v_lshl_add_u64 v[8:9], v[8:9], 0, s[90:91]
	v_add_f32_e32 v4, 1.0, v4
	v_add_f32_e32 v5, 1.0, v5
	v_lshl_add_u64 v[8:9], v[8:9], 0, v[194:195]
	v_rcp_f32_e32 v4, v4
	v_rcp_f32_e32 v5, v5
	global_store_dwordx4 v[8:9], v[12:15], off
	s_nop 1
	v_cvt_pk_bf16_f32 v4, v4, v5
	v_exp_f32_e32 v5, v6
	v_exp_f32_e32 v6, v7
	v_exp_f32_e32 v0, v0
	v_exp_f32_e32 v1, v1
	v_add_f32_e32 v5, 1.0, v5
	v_add_f32_e32 v6, 1.0, v6
	v_add_f32_e32 v0, 1.0, v0
	v_add_f32_e32 v1, 1.0, v1
	v_rcp_f32_e32 v5, v5
	v_rcp_f32_e32 v6, v6
	v_rcp_f32_e32 v0, v0
	v_rcp_f32_e32 v1, v1
	s_nop 1
	v_cvt_pk_bf16_f32 v5, v5, v6
	s_nop 1
	v_cvt_pk_bf16_f32 v6, v0, v1
	v_exp_f32_e32 v0, v2
	v_exp_f32_e32 v1, v3
	s_and_b64 vcc, exec, s[4:5]
	s_mov_b32 s2, s30
	v_add_f32_e32 v0, 1.0, v0
	v_add_f32_e32 v1, 1.0, v1
	s_mov_b32 s3, s29
	s_mov_b64 s[12:13], s[8:9]
	s_mov_b64 s[10:11], s[6:7]
	v_rcp_f32_e32 v0, v0
	v_rcp_f32_e32 v1, v1
	s_nop 1
	v_cvt_pk_bf16_f32 v7, v0, v1
	global_store_dwordx4 v[8:9], v[4:7], off offset:256
	s_cbranch_vccz .LBB0_601
	s_waitcnt vmcnt(0)
	s_cmpk_gt_u32 s16, 0xff
	s_branch .LBB0_608
	s_barrier

.LBB0_670:
	s_add_i32 s44, s14, 2
	s_add_u32 s15, s8, 0xfffc0080
	s_addc_u32 s16, s9, -1
	s_add_i32 s45, 0, 0x10000
	v_add_u32_e32 v140, s45, v237
	ds_read_b128 v[128:131], v140
	ds_read_b128 v[132:135], v140 offset:1024
	ds_read_b128 v[136:139], v140 offset:2048
	ds_read_b128 v[140:143], v140 offset:3072
	s_cmp_eq_u32 s41, s14
	s_cselect_b32 s14, s12, s42
	s_cselect_b32 s17, s11, s16
	s_cselect_b32 s16, s10, s15
	s_cselect_b32 s15, s13, s43
	v_lshl_add_u64 v[176:177], s[8:9], 0, v[206:207]
	s_add_i32 m0, s24, 0xc000
	ds_read_b128 v[144:147], v242
	ds_read_b128 v[148:151], v242 offset:1024
	ds_read_b128 v[152:155], v242 offset:2048
	ds_read_b128 v[156:159], v242 offset:3072
	ds_read_b128 v[160:163], v242 offset:4096
	ds_read_b128 v[164:167], v242 offset:5120
	ds_read_b128 v[168:171], v242 offset:6144
	ds_read_b128 v[172:175], v242 offset:7168
	global_load_lds_dwordx4 v[176:177], off
	v_lshl_add_u64 v[176:177], s[8:9], 0, v[208:209]
	s_add_i32 m0, s24, 0xe000
	s_nop 0
	global_load_lds_dwordx4 v[176:177], off
	s_waitcnt lgkmcnt(8)
	s_barrier
	s_waitcnt lgkmcnt(0)
	s_setprio 1
	s_waitcnt lgkmcnt(0)
	v_mfma_f32_16x16x32_bf16 v[124:127], v[128:131], v[144:147], v[124:127]
	v_mfma_f32_16x16x32_bf16 v[120:123], v[136:139], v[144:147], v[120:123]
	v_mfma_f32_16x16x32_bf16 v[112:115], v[128:131], v[152:155], v[112:115]
	v_mfma_f32_16x16x32_bf16 v[104:107], v[136:139], v[152:155], v[104:107]
	v_mfma_f32_16x16x32_bf16 v[96:99], v[128:131], v[160:163], v[96:99]
	v_mfma_f32_16x16x32_bf16 v[88:91], v[136:139], v[160:163], v[88:91]
	v_mfma_f32_16x16x32_bf16 v[80:83], v[128:131], v[168:171], v[80:83]
	v_mfma_f32_16x16x32_bf16 v[72:75], v[136:139], v[168:171], v[72:75]
	v_mfma_f32_16x16x32_bf16 v[124:127], v[132:135], v[148:151], v[124:127]
	v_mfma_f32_16x16x32_bf16 v[120:123], v[140:143], v[148:151], v[120:123]
	v_mfma_f32_16x16x32_bf16 v[112:115], v[132:135], v[156:159], v[112:115]
	v_mfma_f32_16x16x32_bf16 v[104:107], v[140:143], v[156:159], v[104:107]
	v_mfma_f32_16x16x32_bf16 v[96:99], v[132:135], v[164:167], v[96:99]
	v_mfma_f32_16x16x32_bf16 v[88:91], v[140:143], v[164:167], v[88:91]
	v_mfma_f32_16x16x32_bf16 v[80:83], v[132:135], v[172:175], v[80:83]
	v_mfma_f32_16x16x32_bf16 v[72:75], v[140:143], v[172:175], v[72:75]
	s_setprio 0
	s_barrier
	s_add_i32 s48, 0, 0x14000
	s_add_i32 s45, s45, s23
	v_add_u32_e32 v188, s48, v237
	v_lshl_add_u64 v[192:193], s[14:15], 0, v[194:195]
	s_mov_b32 m0, s45
	ds_read_b128 v[176:179], v188
	ds_read_b128 v[180:183], v188 offset:1024
	ds_read_b128 v[184:187], v188 offset:2048
	ds_read_b128 v[188:191], v188 offset:3072
	global_load_lds_dwordx4 v[192:193], off
	v_lshl_add_u64 v[210:211], s[14:15], 0, v[204:205]
	s_add_i32 m0, s45, 0x2000
	s_nop 0
	global_load_lds_dwordx4 v[210:211], off
	s_barrier
	s_waitcnt lgkmcnt(0)
	s_setprio 1
	s_waitcnt lgkmcnt(0)
	v_mfma_f32_16x16x32_bf16 v[116:119], v[176:179], v[144:147], v[116:119]
	v_mfma_f32_16x16x32_bf16 v[108:111], v[184:187], v[144:147], v[108:111]
	v_mfma_f32_16x16x32_bf16 v[100:103], v[176:179], v[152:155], v[100:103]
	v_mfma_f32_16x16x32_bf16 v[92:95], v[184:187], v[152:155], v[92:95]
	v_mfma_f32_16x16x32_bf16 v[84:87], v[176:179], v[160:163], v[84:87]
	v_mfma_f32_16x16x32_bf16 v[76:79], v[184:187], v[160:163], v[76:79]
	v_mfma_f32_16x16x32_bf16 v[68:71], v[176:179], v[168:171], v[68:71]
	v_mfma_f32_16x16x32_bf16 v[64:67], v[184:187], v[168:171], v[64:67]
	v_mfma_f32_16x16x32_bf16 v[116:119], v[180:183], v[148:151], v[116:119]
	v_mfma_f32_16x16x32_bf16 v[108:111], v[188:191], v[148:151], v[108:111]
	v_mfma_f32_16x16x32_bf16 v[100:103], v[180:183], v[156:159], v[100:103]
	v_mfma_f32_16x16x32_bf16 v[92:95], v[188:191], v[156:159], v[92:95]
	v_mfma_f32_16x16x32_bf16 v[84:87], v[180:183], v[164:167], v[84:87]
	v_mfma_f32_16x16x32_bf16 v[76:79], v[188:191], v[164:167], v[76:79]
	v_mfma_f32_16x16x32_bf16 v[68:71], v[180:183], v[172:175], v[68:71]
	v_mfma_f32_16x16x32_bf16 v[64:67], v[188:191], v[172:175], v[64:67]
	s_setprio 0
	s_mov_b32 m0, s24
	v_lshl_add_u64 v[212:213], s[16:17], 0, v[194:195]
	s_barrier
	ds_read_b128 v[144:147], v242 offset:16384
	ds_read_b128 v[148:151], v242 offset:17408
	ds_read_b128 v[152:155], v242 offset:18432
	ds_read_b128 v[156:159], v242 offset:19456
	ds_read_b128 v[160:163], v242 offset:20480
	ds_read_b128 v[164:167], v242 offset:21504
	ds_read_b128 v[168:171], v242 offset:22528
	ds_read_b128 v[172:175], v242 offset:23552
	global_load_lds_dwordx4 v[212:213], off
	v_lshl_add_u64 v[214:215], s[16:17], 0, v[204:205]
	s_mov_b32 m0, s25
	s_nop 0
	global_load_lds_dwordx4 v[214:215], off
	s_barrier
	s_waitcnt lgkmcnt(0)
	s_setprio 1
	s_waitcnt lgkmcnt(0)
	v_mfma_f32_16x16x32_bf16 v[60:63], v[128:131], v[144:147], v[60:63]
	v_mfma_f32_16x16x32_bf16 v[56:59], v[136:139], v[144:147], v[56:59]
	v_mfma_f32_16x16x32_bf16 v[48:51], v[128:131], v[152:155], v[48:51]
	v_mfma_f32_16x16x32_bf16 v[40:43], v[136:139], v[152:155], v[40:43]
	v_mfma_f32_16x16x32_bf16 v[32:35], v[128:131], v[160:163], v[32:35]
	v_mfma_f32_16x16x32_bf16 v[24:27], v[136:139], v[160:163], v[24:27]
	v_mfma_f32_16x16x32_bf16 v[16:19], v[128:131], v[168:171], v[16:19]
	v_mfma_f32_16x16x32_bf16 v[8:11], v[136:139], v[168:171], v[8:11]
	v_mfma_f32_16x16x32_bf16 v[60:63], v[132:135], v[148:151], v[60:63]
	v_mfma_f32_16x16x32_bf16 v[56:59], v[140:143], v[148:151], v[56:59]
	v_mfma_f32_16x16x32_bf16 v[48:51], v[132:135], v[156:159], v[48:51]
	v_mfma_f32_16x16x32_bf16 v[40:43], v[140:143], v[156:159], v[40:43]
	v_mfma_f32_16x16x32_bf16 v[32:35], v[132:135], v[164:167], v[32:35]
	v_mfma_f32_16x16x32_bf16 v[24:27], v[140:143], v[164:167], v[24:27]
	v_mfma_f32_16x16x32_bf16 v[16:19], v[132:135], v[172:175], v[16:19]
	v_mfma_f32_16x16x32_bf16 v[8:11], v[140:143], v[172:175], v[8:11]
	s_setprio 0
	s_barrier
	s_add_u32 s46, s14, 0x40000
	s_addc_u32 s47, s15, 0
	s_add_i32 s45, s48, s23
	v_lshl_add_u64 v[128:129], s[46:47], 0, v[194:195]
	s_mov_b32 m0, s45
	s_nop 0
	global_load_lds_dwordx4 v[128:129], off
	v_lshl_add_u64 v[128:129], s[46:47], 0, v[204:205]
	s_add_i32 m0, s45, 0x2000
	s_nop 0
	global_load_lds_dwordx4 v[128:129], off
	s_waitcnt vmcnt(6)
	s_barrier
	s_setprio 1
	v_mfma_f32_16x16x32_bf16 v[52:55], v[176:179], v[144:147], v[52:55]
	v_mfma_f32_16x16x32_bf16 v[44:47], v[184:187], v[144:147], v[44:47]
	v_mfma_f32_16x16x32_bf16 v[36:39], v[176:179], v[152:155], v[36:39]
	v_mfma_f32_16x16x32_bf16 v[28:31], v[184:187], v[152:155], v[28:31]
	v_mfma_f32_16x16x32_bf16 v[20:23], v[176:179], v[160:163], v[20:23]
	v_mfma_f32_16x16x32_bf16 v[12:15], v[184:187], v[160:163], v[12:15]
	v_mfma_f32_16x16x32_bf16 v[4:7], v[176:179], v[168:171], v[4:7]
	v_mfma_f32_16x16x32_bf16 v[0:3], v[184:187], v[168:171], v[0:3]
	v_mfma_f32_16x16x32_bf16 v[52:55], v[180:183], v[148:151], v[52:55]
	v_mfma_f32_16x16x32_bf16 v[44:47], v[188:191], v[148:151], v[44:47]
	v_mfma_f32_16x16x32_bf16 v[36:39], v[180:183], v[156:159], v[36:39]
	v_mfma_f32_16x16x32_bf16 v[28:31], v[188:191], v[156:159], v[28:31]
	v_mfma_f32_16x16x32_bf16 v[20:23], v[180:183], v[164:167], v[20:23]
	v_mfma_f32_16x16x32_bf16 v[12:15], v[188:191], v[164:167], v[12:15]
	v_mfma_f32_16x16x32_bf16 v[4:7], v[180:183], v[172:175], v[4:7]
	v_mfma_f32_16x16x32_bf16 v[0:3], v[188:191], v[172:175], v[0:3]
	s_setprio 0
	s_add_i32 s45, 0, 0x18000
	v_add_u32_e32 v140, s45, v237
	s_barrier
	ds_read_b128 v[128:131], v140
	ds_read_b128 v[132:135], v140 offset:1024
	ds_read_b128 v[136:139], v140 offset:2048
	ds_read_b128 v[140:143], v140 offset:3072
	s_add_u32 s16, s16, 0x40000
	s_addc_u32 s17, s17, 0
	s_mov_b32 m0, s26
	v_lshl_add_u64 v[176:177], s[16:17], 0, v[194:195]
	ds_read_b128 v[144:147], v242 offset:32768
	ds_read_b128 v[148:151], v242 offset:33792
	ds_read_b128 v[152:155], v242 offset:34816
	ds_read_b128 v[156:159], v242 offset:35840
	ds_read_b128 v[160:163], v242 offset:36864
	ds_read_b128 v[164:167], v242 offset:37888
	ds_read_b128 v[168:171], v242 offset:38912
	ds_read_b128 v[172:175], v242 offset:39936
	global_load_lds_dwordx4 v[176:177], off
	v_lshl_add_u64 v[176:177], s[16:17], 0, v[204:205]
	s_mov_b32 m0, s27
	s_nop 0
	global_load_lds_dwordx4 v[176:177], off
	s_waitcnt lgkmcnt(8)
	s_barrier
	s_waitcnt lgkmcnt(0)
	s_setprio 1
	s_waitcnt lgkmcnt(0)
	v_mfma_f32_16x16x32_bf16 v[124:127], v[128:131], v[144:147], v[124:127]
	v_mfma_f32_16x16x32_bf16 v[120:123], v[136:139], v[144:147], v[120:123]
	v_mfma_f32_16x16x32_bf16 v[112:115], v[128:131], v[152:155], v[112:115]
	v_mfma_f32_16x16x32_bf16 v[104:107], v[136:139], v[152:155], v[104:107]
	v_mfma_f32_16x16x32_bf16 v[96:99], v[128:131], v[160:163], v[96:99]
	v_mfma_f32_16x16x32_bf16 v[88:91], v[136:139], v[160:163], v[88:91]
	v_mfma_f32_16x16x32_bf16 v[80:83], v[128:131], v[168:171], v[80:83]
	v_mfma_f32_16x16x32_bf16 v[72:75], v[136:139], v[168:171], v[72:75]
	v_mfma_f32_16x16x32_bf16 v[124:127], v[132:135], v[148:151], v[124:127]
	v_mfma_f32_16x16x32_bf16 v[120:123], v[140:143], v[148:151], v[120:123]
	v_mfma_f32_16x16x32_bf16 v[112:115], v[132:135], v[156:159], v[112:115]
	v_mfma_f32_16x16x32_bf16 v[104:107], v[140:143], v[156:159], v[104:107]
	v_mfma_f32_16x16x32_bf16 v[96:99], v[132:135], v[164:167], v[96:99]
	v_mfma_f32_16x16x32_bf16 v[88:91], v[140:143], v[164:167], v[88:91]
	v_mfma_f32_16x16x32_bf16 v[80:83], v[132:135], v[172:175], v[80:83]
	v_mfma_f32_16x16x32_bf16 v[72:75], v[140:143], v[172:175], v[72:75]
	s_setprio 0
	s_barrier
	s_add_i32 s16, 0, 0x1c000
	s_add_i32 s17, s45, s23
	v_add_u32_e32 v188, s16, v237
	v_lshl_add_u64 v[192:193], v[192:193], 0, s[82:83]
	s_mov_b32 m0, s17
	ds_read_b128 v[176:179], v188
	ds_read_b128 v[180:183], v188 offset:1024
	ds_read_b128 v[184:187], v188 offset:2048
	ds_read_b128 v[188:191], v188 offset:3072
	global_load_lds_dwordx4 v[192:193], off
	v_lshl_add_u64 v[192:193], v[210:211], 0, s[82:83]
	s_add_i32 m0, s17, 0x2000
	s_nop 0
	global_load_lds_dwordx4 v[192:193], off
	s_barrier
	s_waitcnt lgkmcnt(0)
	s_setprio 1
	s_waitcnt lgkmcnt(0)
	v_mfma_f32_16x16x32_bf16 v[116:119], v[176:179], v[144:147], v[116:119]
	v_mfma_f32_16x16x32_bf16 v[108:111], v[184:187], v[144:147], v[108:111]
	v_mfma_f32_16x16x32_bf16 v[100:103], v[176:179], v[152:155], v[100:103]
	v_mfma_f32_16x16x32_bf16 v[92:95], v[184:187], v[152:155], v[92:95]
	v_mfma_f32_16x16x32_bf16 v[84:87], v[176:179], v[160:163], v[84:87]
	v_mfma_f32_16x16x32_bf16 v[76:79], v[184:187], v[160:163], v[76:79]
	v_mfma_f32_16x16x32_bf16 v[68:71], v[176:179], v[168:171], v[68:71]
	v_mfma_f32_16x16x32_bf16 v[64:67], v[184:187], v[168:171], v[64:67]
	v_mfma_f32_16x16x32_bf16 v[116:119], v[180:183], v[148:151], v[116:119]
	v_mfma_f32_16x16x32_bf16 v[108:111], v[188:191], v[148:151], v[108:111]
	v_mfma_f32_16x16x32_bf16 v[100:103], v[180:183], v[156:159], v[100:103]
	v_mfma_f32_16x16x32_bf16 v[92:95], v[188:191], v[156:159], v[92:95]
	v_mfma_f32_16x16x32_bf16 v[84:87], v[180:183], v[164:167], v[84:87]
	v_mfma_f32_16x16x32_bf16 v[76:79], v[188:191], v[164:167], v[76:79]
	v_mfma_f32_16x16x32_bf16 v[68:71], v[180:183], v[172:175], v[68:71]
	v_mfma_f32_16x16x32_bf16 v[64:67], v[188:191], v[172:175], v[64:67]
	s_setprio 0
	s_mov_b32 m0, s28
	v_lshl_add_u64 v[192:193], v[212:213], 0, s[82:83]
	s_barrier
	ds_read_b128 v[144:147], v242 offset:49152
	ds_read_b128 v[148:151], v242 offset:50176
	ds_read_b128 v[152:155], v242 offset:51200
	ds_read_b128 v[156:159], v242 offset:52224
	ds_read_b128 v[160:163], v242 offset:53248
	ds_read_b128 v[164:167], v242 offset:54272
	ds_read_b128 v[168:171], v242 offset:55296
	ds_read_b128 v[172:175], v242 offset:56320
	global_load_lds_dwordx4 v[192:193], off
	v_lshl_add_u64 v[192:193], v[214:215], 0, s[82:83]
	s_mov_b32 m0, s29
	s_nop 0
	global_load_lds_dwordx4 v[192:193], off
	s_barrier
	s_waitcnt lgkmcnt(0)
	s_setprio 1
	s_waitcnt lgkmcnt(0)
	v_mfma_f32_16x16x32_bf16 v[60:63], v[128:131], v[144:147], v[60:63]
	v_mfma_f32_16x16x32_bf16 v[56:59], v[136:139], v[144:147], v[56:59]
	v_mfma_f32_16x16x32_bf16 v[48:51], v[128:131], v[152:155], v[48:51]
	v_mfma_f32_16x16x32_bf16 v[40:43], v[136:139], v[152:155], v[40:43]
	v_mfma_f32_16x16x32_bf16 v[32:35], v[128:131], v[160:163], v[32:35]
	v_mfma_f32_16x16x32_bf16 v[24:27], v[136:139], v[160:163], v[24:27]
	v_mfma_f32_16x16x32_bf16 v[16:19], v[128:131], v[168:171], v[16:19]
	v_mfma_f32_16x16x32_bf16 v[8:11], v[136:139], v[168:171], v[8:11]
	v_mfma_f32_16x16x32_bf16 v[60:63], v[132:135], v[148:151], v[60:63]
	v_mfma_f32_16x16x32_bf16 v[56:59], v[140:143], v[148:151], v[56:59]
	v_mfma_f32_16x16x32_bf16 v[48:51], v[132:135], v[156:159], v[48:51]
	v_mfma_f32_16x16x32_bf16 v[40:43], v[140:143], v[156:159], v[40:43]
	v_mfma_f32_16x16x32_bf16 v[32:35], v[132:135], v[164:167], v[32:35]
	v_mfma_f32_16x16x32_bf16 v[24:27], v[140:143], v[164:167], v[24:27]
	v_mfma_f32_16x16x32_bf16 v[16:19], v[132:135], v[172:175], v[16:19]
	v_mfma_f32_16x16x32_bf16 v[8:11], v[140:143], v[172:175], v[8:11]
	s_setprio 0
	s_barrier
	s_add_u32 s14, s14, 0x40080
	s_addc_u32 s15, s15, 0
	s_add_i32 s16, s16, s23
	v_lshl_add_u64 v[128:129], s[14:15], 0, v[194:195]
	s_mov_b32 m0, s16
	s_nop 0
	global_load_lds_dwordx4 v[128:129], off
	v_lshl_add_u64 v[128:129], s[14:15], 0, v[204:205]
	s_add_i32 m0, s16, 0x2000
	s_nop 0
	global_load_lds_dwordx4 v[128:129], off
	s_waitcnt vmcnt(6)
	s_barrier
	s_setprio 1
	v_mfma_f32_16x16x32_bf16 v[52:55], v[176:179], v[144:147], v[52:55]
	v_mfma_f32_16x16x32_bf16 v[44:47], v[184:187], v[144:147], v[44:47]
	v_mfma_f32_16x16x32_bf16 v[36:39], v[176:179], v[152:155], v[36:39]
	v_mfma_f32_16x16x32_bf16 v[28:31], v[184:187], v[152:155], v[28:31]
	v_mfma_f32_16x16x32_bf16 v[20:23], v[176:179], v[160:163], v[20:23]
	v_mfma_f32_16x16x32_bf16 v[12:15], v[184:187], v[160:163], v[12:15]
	v_mfma_f32_16x16x32_bf16 v[4:7], v[176:179], v[168:171], v[4:7]
	v_mfma_f32_16x16x32_bf16 v[0:3], v[184:187], v[168:171], v[0:3]
	v_mfma_f32_16x16x32_bf16 v[52:55], v[180:183], v[148:151], v[52:55]
	v_mfma_f32_16x16x32_bf16 v[44:47], v[188:191], v[148:151], v[44:47]
	v_mfma_f32_16x16x32_bf16 v[36:39], v[180:183], v[156:159], v[36:39]
	v_mfma_f32_16x16x32_bf16 v[28:31], v[188:191], v[156:159], v[28:31]
	v_mfma_f32_16x16x32_bf16 v[20:23], v[180:183], v[164:167], v[20:23]
	v_mfma_f32_16x16x32_bf16 v[12:15], v[188:191], v[164:167], v[12:15]
	v_mfma_f32_16x16x32_bf16 v[4:7], v[180:183], v[172:175], v[4:7]
	v_mfma_f32_16x16x32_bf16 v[0:3], v[188:191], v[172:175], v[0:3]
	s_setprio 0
	s_add_u32 s8, s8, 0x100
	s_addc_u32 s9, s9, 0
	s_add_u32 s42, s42, 0x100
	s_addc_u32 s43, s43, 0
	s_cmp_ge_i32 s44, s40
	s_mov_b32 s14, s44
	s_barrier
	s_cbranch_scc0 .LBB0_670
	s_and_b64 vcc, exec, s[6:7]
	s_cbranch_vccz .Lal_merge
	s_cmpk_gt_u32 s2, 0xff
	s_cbranch_scc1 .Lal_merge
	s_barrier
.Lal_merge:
	s_lshl_b32 s8, s37, 10
	s_ashr_i32 s9, s8, 31
	s_cmp_gt_i32 s37, 0
	s_cselect_b64 s[16:17], -1, 0
	s_lshl_b32 s39, s39, 8
	s_lshl_b64 s[8:9], s[8:9], 1
	s_add_u32 s14, s3, s8
	s_addc_u32 s15, s18, s9
	v_add_u32_e32 v210, s39, v236
	v_lshl_or_b32 v212, s38, 8, v241
	v_mov_b64_e32 v[128:129], s[14:15]
	v_mad_i64_i32 v[128:129], s[8:9], v210, s81, v[128:129]
	v_ashrrev_i32_e32 v213, 31, v212
	v_lshl_add_u64 v[130:131], v[212:213], 1, v[128:129]
	global_load_dwordx4 v[186:189], v[130:131], off
	v_ashrrev_i32_e32 v211, 31, v210
	v_lshlrev_b64 v[128:129], 11, v[210:211]
	v_lshl_add_u64 v[214:215], s[0:1], 0, v[128:129]
	s_cmp_lt_i32 s37, 1
	v_lshl_add_u64 v[128:129], v[212:213], 1, v[214:215]
	s_cbranch_scc1 .LBB0_673
	global_load_dwordx4 v[190:193], v[128:129], off
	s_branch .LBB0_674

.LBB0_704:
	s_waitcnt vmcnt(0)
	s_cmpk_gt_u32 s2, 0xff
	s_branch .LBB0_706
	s_barrier
